# v14 + pair-pass twiddles from a single sin/cos: other 14 factors by complex products with exact 16th-root constants (f32)
# speedup vs baseline: 1.0367x; 1.0006x over previous
; DI float2 twid(float r) { return float2{__builtin_amdgcn_cosf(r), -__builtin_amdgcn_sinf(r)}; }
; DI void bfly_fwd(float2 a0, float2 a1, float2 a2, float2 a3, float r, float2& o0, float2& o1, float2& o2, float2& o3) {
;   float2 t0 = {a0.x + a2.x, a0.y + a2.y}, t1 = {a0.x - a2.x, a0.y - a2.y}, t2 = {a1.x + a3.x, a1.y + a3.y}, t3 = {a1.x - a3.x, a1.y - a3.y};
;   float2 b0 = {t0.x + t2.x, t0.y + t2.y}, b2 = {t0.x - t2.x, t0.y - t2.y}, b1 = {t1.x + t3.y, t1.y - t3.x}, b3 = {t1.x - t3.y, t1.y + t3.x};
;   float2 w1 = twid(r), w2 = cmul(w1, w1), w3 = cmul(w2, w1);
;   o0 = b0; o1 = cmul(b1, w1); o2 = cmul(b2, w2); o3 = cmul(b3, w3);
; }
;   const int lq2 = lq1 - 2, Q1 = 1 << lq1, Q2 = 1 << lq2; const float invM1 = 1.f / (float)(4 << lq1), invM2 = 1.f / (float)(4 << lq2);
;   for (int gg = tid; gg < NBT * (N / 16); gg += NTHR) { const int g = gg & (N / 16 - 1); float2* z = z0 + (gg / (N / 16)) * N; const int jp = g & (Q2 - 1), base = ((g >> lq2) << (lq2 + 4)) + jp; float2 x[4][4];
; #pragma unroll
;     for (int q1 = 0; q1 < 4; ++q1)
; #pragma unroll
;       for (int q2 = 0; q2 < 4; ++q2) x[q1][q2] = z[base + q1 * Q1 + q2 * Q2];
; #pragma unroll
;     for (int q2 = 0; q2 < 4; ++q2) bfly_fwd(x[0][q2], x[1][q2], x[2][q2], x[3][q2], (float)(jp + q2 * Q2) * invM1, x[0][q2], x[1][q2], x[2][q2], x[3][q2]);
; #pragma unroll
;     for (int q1 = 0; q1 < 4; ++q1) bfly_fwd(x[q1][0], x[q1][1], x[q1][2], x[q1][3], (float)jp * invM2, x[q1][0], x[q1][1], x[q1][2], x[q1][3]);
.LBB0_1488:
	s_or_b64 exec, exec, s[0:1]
	s_add_i32 s0, 16, 0x20000
	v_mov_b32_e32 v0, s0
	v_readlane_b32 s0, v240, 48
	s_or_b32 s96, s21, s75
	s_waitcnt lgkmcnt(0)
	s_barrier
	ds_read_b128 v[6:9], v0
	v_mov_b32_e32 v0, s0
	s_lshl_b64 s[0:1], s[96:97], 2
	s_add_u32 s0, s18, s0
	s_addc_u32 s1, s19, s1
	ds_read_b128 v[2:5], v0
	global_load_dword v0, v1, s[0:1]
	s_movk_i32 s0, 0x200
	v_cmp_gt_i32_e32 vcc, s0, v10
	v_lshlrev_b32_e32 v11, 7, v10
	s_and_saveexec_b64 s[0:1], vcc
	s_cbranch_execz .LBB0_1491
	s_movk_i32 s8, 0x100
	v_and_b32_e32 v13, 0x8000, v11
	v_lshlrev_b32_sdwa v16, v151, v10 dst_sel:DWORD dst_unused:UNUSED_PAD src0_sel:DWORD src1_sel:BYTE_0
	v_add3_u32 v72, 16, v13, v16
	s_movk_i32 s8, 0x200
	s_movk_i32 s8, 0x300
	s_mov_b64 s[10:11], 0
	v_mov_b32_e32 v73, v10
	v_and_b32_e32 v241, 0xff, v73
	v_cvt_f32_u32_e32 v250, v241
	v_mul_f32_e32 v250, 0x39800000, v250
	v_cos_f32_e32 v218, v250
	v_sin_f32_e32 v219, v250
	s_nop 1
	v_xor_b32_e32 v219, 0x80000000, v219
	s_nop 0
	v_pk_mul_f32 v[126:127], v[218:219], v[218:219] op_sel:[1,1] op_sel_hi:[1,0]
	s_nop 0
	v_pk_fma_f32 v[220:221], v[218:219], v[218:219], v[126:127] op_sel_hi:[0,1,1] neg_lo:[0,0,1]
	s_nop 0
	v_pk_mul_f32 v[126:127], v[220:221], v[218:219] op_sel:[1,1] op_sel_hi:[1,0]
	s_nop 0
	v_pk_fma_f32 v[222:223], v[220:221], v[218:219], v[126:127] op_sel_hi:[0,1,1] neg_lo:[0,0,1]
	v_pk_mul_f32 v[126:127], v[220:221], v[220:221] op_sel:[1,1] op_sel_hi:[1,0]
	s_nop 0
	v_pk_fma_f32 v[244:245], v[220:221], v[220:221], v[126:127] op_sel_hi:[0,1,1] neg_lo:[0,0,1]
	s_nop 0
	v_mul_f32_e32 v241, 0x3ec3ef15, v219
	v_mul_f32_e32 v250, 0xbec3ef15, v218
	v_fmamk_f32 v224, v218, 0x3f6c835e, v241
	v_fmamk_f32 v225, v219, 0x3f6c835e, v250
	v_mul_f32_e32 v241, 0x3f3504f3, v219
	v_mul_f32_e32 v250, 0xbf3504f3, v218
	v_fmamk_f32 v230, v218, 0x3f3504f3, v241
	v_fmamk_f32 v231, v219, 0x3f3504f3, v250
	v_mul_f32_e32 v241, 0x3f6c835e, v219
	v_mul_f32_e32 v250, 0xbf6c835e, v218
	v_fmamk_f32 v236, v218, 0x3ec3ef15, v241
	v_fmamk_f32 v237, v219, 0x3ec3ef15, v250
	v_mul_f32_e32 v241, 0x3f3504f3, v221
	v_mul_f32_e32 v250, 0xbf3504f3, v220
	v_fmamk_f32 v226, v220, 0x3f3504f3, v241
	v_fmamk_f32 v227, v221, 0x3f3504f3, v250
	v_mul_f32_e32 v241, 0x3f800000, v221
	v_mul_f32_e32 v250, 0xbf800000, v220
	v_fmamk_f32 v232, v220, 0x00000000, v241
	v_fmamk_f32 v233, v221, 0x00000000, v250
	v_mul_f32_e32 v241, 0x3f3504f3, v221
	v_mul_f32_e32 v250, 0xbf3504f3, v220
	v_fmamk_f32 v238, v220, 0xbf3504f3, v241
	v_fmamk_f32 v239, v221, 0xbf3504f3, v250
	v_mul_f32_e32 v241, 0x3f6c835e, v223
	v_mul_f32_e32 v250, 0xbf6c835e, v222
	v_fmamk_f32 v228, v222, 0x3ec3ef15, v241
	v_fmamk_f32 v229, v223, 0x3ec3ef15, v250
	v_mul_f32_e32 v241, 0x3f3504f3, v223
	v_mul_f32_e32 v250, 0xbf3504f3, v222
	v_fmamk_f32 v234, v222, 0xbf3504f3, v241
	v_fmamk_f32 v235, v223, 0xbf3504f3, v250
	v_mul_f32_e32 v241, 0xbec3ef15, v223
	v_mul_f32_e32 v250, 0x3ec3ef15, v222
	v_fmamk_f32 v242, v222, 0xbf6c835e, v241
	v_fmamk_f32 v243, v223, 0xbf6c835e, v250
	v_pk_mul_f32 v[126:127], v[244:245], v[244:245] op_sel:[1,1] op_sel_hi:[1,0]
	s_nop 0
	v_pk_fma_f32 v[246:247], v[244:245], v[244:245], v[126:127] op_sel_hi:[0,1,1] neg_lo:[0,0,1]
	s_nop 0
	v_pk_mul_f32 v[126:127], v[246:247], v[244:245] op_sel:[1,1] op_sel_hi:[1,0]
	s_nop 0
	v_pk_fma_f32 v[248:249], v[246:247], v[244:245], v[126:127] op_sel_hi:[0,1,1] neg_lo:[0,0,1]
	s_nop 0

; DI float2 twid(float r) { return float2{__builtin_amdgcn_cosf(r), -__builtin_amdgcn_sinf(r)}; }
; DI void bfly_fwd(float2 a0, float2 a1, float2 a2, float2 a3, float r, float2& o0, float2& o1, float2& o2, float2& o3) {
;   float2 t0 = {a0.x + a2.x, a0.y + a2.y}, t1 = {a0.x - a2.x, a0.y - a2.y}, t2 = {a1.x + a3.x, a1.y + a3.y}, t3 = {a1.x - a3.x, a1.y - a3.y};
;   float2 b0 = {t0.x + t2.x, t0.y + t2.y}, b2 = {t0.x - t2.x, t0.y - t2.y}, b1 = {t1.x + t3.y, t1.y - t3.x}, b3 = {t1.x - t3.y, t1.y + t3.x};
;   float2 w1 = twid(r), w2 = cmul(w1, w1), w3 = cmul(w2, w1);
;   o0 = b0; o1 = cmul(b1, w1); o2 = cmul(b2, w2); o3 = cmul(b3, w3);
; }
;   const int lq2 = lq1 - 2, Q1 = 1 << lq1, Q2 = 1 << lq2; const float invM1 = 1.f / (float)(4 << lq1), invM2 = 1.f / (float)(4 << lq2);
;   for (int gg = tid; gg < NBT * (N / 16); gg += NTHR) { const int g = gg & (N / 16 - 1); float2* z = z0 + (gg / (N / 16)) * N; const int jp = g & (Q2 - 1), base = ((g >> lq2) << (lq2 + 4)) + jp; float2 x[4][4];
; #pragma unroll
;     for (int q1 = 0; q1 < 4; ++q1)
; #pragma unroll
;       for (int q2 = 0; q2 < 4; ++q2) x[q1][q2] = z[base + q1 * Q1 + q2 * Q2];
; #pragma unroll
;     for (int q2 = 0; q2 < 4; ++q2) bfly_fwd(x[0][q2], x[1][q2], x[2][q2], x[3][q2], (float)(jp + q2 * Q2) * invM1, x[0][q2], x[1][q2], x[2][q2], x[3][q2]);
; #pragma unroll
;     for (int q1 = 0; q1 < 4; ++q1) bfly_fwd(x[q1][0], x[q1][1], x[q1][2], x[q1][3], (float)jp * invM2, x[q1][0], x[q1][1], x[q1][2], x[q1][3]);
.LBB0_1491:
	s_or_b64 exec, exec, s[0:1]
	s_waitcnt lgkmcnt(0)
	s_barrier
	s_and_saveexec_b64 s[0:1], vcc
	s_cbranch_execz .LBB0_1494
	v_and_b32_e32 v13, 15, v10
	v_and_b32_e32 v11, 0xf800, v11
	v_lshlrev_b32_e32 v16, 3, v13
	v_add3_u32 v11, 16, v11, v16
	s_mov_b64 s[8:9], 0
	v_mov_b32_e32 v72, v10
	v_and_b32_e32 v241, 0xf, v72
	v_cvt_f32_u32_e32 v250, v241
	v_mul_f32_e32 v250, 0x3b800000, v250
	v_cos_f32_e32 v218, v250
	v_sin_f32_e32 v219, v250
	s_nop 1
	v_xor_b32_e32 v219, 0x80000000, v219
	s_nop 0
	v_pk_mul_f32 v[124:125], v[218:219], v[218:219] op_sel:[1,1] op_sel_hi:[1,0]
	s_nop 0
	v_pk_fma_f32 v[220:221], v[218:219], v[218:219], v[124:125] op_sel_hi:[0,1,1] neg_lo:[0,0,1]
	s_nop 0
	v_pk_mul_f32 v[124:125], v[220:221], v[218:219] op_sel:[1,1] op_sel_hi:[1,0]
	s_nop 0
	v_pk_fma_f32 v[222:223], v[220:221], v[218:219], v[124:125] op_sel_hi:[0,1,1] neg_lo:[0,0,1]
	v_pk_mul_f32 v[124:125], v[220:221], v[220:221] op_sel:[1,1] op_sel_hi:[1,0]
	s_nop 0
	v_pk_fma_f32 v[244:245], v[220:221], v[220:221], v[124:125] op_sel_hi:[0,1,1] neg_lo:[0,0,1]
	s_nop 0
	v_mul_f32_e32 v241, 0x3ec3ef15, v219
	v_mul_f32_e32 v250, 0xbec3ef15, v218
	v_fmamk_f32 v224, v218, 0x3f6c835e, v241
	v_fmamk_f32 v225, v219, 0x3f6c835e, v250
	v_mul_f32_e32 v241, 0x3f3504f3, v219
	v_mul_f32_e32 v250, 0xbf3504f3, v218
	v_fmamk_f32 v230, v218, 0x3f3504f3, v241
	v_fmamk_f32 v231, v219, 0x3f3504f3, v250
	v_mul_f32_e32 v241, 0x3f6c835e, v219
	v_mul_f32_e32 v250, 0xbf6c835e, v218
	v_fmamk_f32 v236, v218, 0x3ec3ef15, v241
	v_fmamk_f32 v237, v219, 0x3ec3ef15, v250
	v_mul_f32_e32 v241, 0x3f3504f3, v221
	v_mul_f32_e32 v250, 0xbf3504f3, v220
	v_fmamk_f32 v226, v220, 0x3f3504f3, v241
	v_fmamk_f32 v227, v221, 0x3f3504f3, v250
	v_mul_f32_e32 v241, 0x3f800000, v221
	v_mul_f32_e32 v250, 0xbf800000, v220
	v_fmamk_f32 v232, v220, 0x00000000, v241
	v_fmamk_f32 v233, v221, 0x00000000, v250
	v_mul_f32_e32 v241, 0x3f3504f3, v221
	v_mul_f32_e32 v250, 0xbf3504f3, v220
	v_fmamk_f32 v238, v220, 0xbf3504f3, v241
	v_fmamk_f32 v239, v221, 0xbf3504f3, v250
	v_mul_f32_e32 v241, 0x3f6c835e, v223
	v_mul_f32_e32 v250, 0xbf6c835e, v222
	v_fmamk_f32 v228, v222, 0x3ec3ef15, v241
	v_fmamk_f32 v229, v223, 0x3ec3ef15, v250
	v_mul_f32_e32 v241, 0x3f3504f3, v223
	v_mul_f32_e32 v250, 0xbf3504f3, v222
	v_fmamk_f32 v234, v222, 0xbf3504f3, v241
	v_fmamk_f32 v235, v223, 0xbf3504f3, v250
	v_mul_f32_e32 v241, 0xbec3ef15, v223
	v_mul_f32_e32 v250, 0x3ec3ef15, v222
	v_fmamk_f32 v242, v222, 0xbf6c835e, v241
	v_fmamk_f32 v243, v223, 0xbf6c835e, v250
	v_pk_mul_f32 v[124:125], v[244:245], v[244:245] op_sel:[1,1] op_sel_hi:[1,0]
	s_nop 0
	v_pk_fma_f32 v[246:247], v[244:245], v[244:245], v[124:125] op_sel_hi:[0,1,1] neg_lo:[0,0,1]
	s_nop 0
	v_pk_mul_f32 v[124:125], v[246:247], v[244:245] op_sel:[1,1] op_sel_hi:[1,0]
	s_nop 0
	v_pk_fma_f32 v[248:249], v[246:247], v[244:245], v[124:125] op_sel_hi:[0,1,1] neg_lo:[0,0,1]
	s_nop 0

; DI float2 twid(float r) { return float2{__builtin_amdgcn_cosf(r), -__builtin_amdgcn_sinf(r)}; }
; DI void bfly_fwd(float2 a0, float2 a1, float2 a2, float2 a3, float r, float2& o0, float2& o1, float2& o2, float2& o3) {
;   float2 t0 = {a0.x + a2.x, a0.y + a2.y}, t1 = {a0.x - a2.x, a0.y - a2.y}, t2 = {a1.x + a3.x, a1.y + a3.y}, t3 = {a1.x - a3.x, a1.y - a3.y};
;   float2 b0 = {t0.x + t2.x, t0.y + t2.y}, b2 = {t0.x - t2.x, t0.y - t2.y}, b1 = {t1.x + t3.y, t1.y - t3.x}, b3 = {t1.x - t3.y, t1.y + t3.x};
;   float2 w1 = twid(r), w2 = cmul(w1, w1), w3 = cmul(w2, w1);
;   o0 = b0; o1 = cmul(b1, w1); o2 = cmul(b2, w2); o3 = cmul(b3, w3);
; }
;   const int lq2 = lq1 - 2, Q1 = 1 << lq1, Q2 = 1 << lq2; const float invM1 = 1.f / (float)(4 << lq1), invM2 = 1.f / (float)(4 << lq2);
;   for (int gg = tid; gg < NBT * (N / 16); gg += NTHR) { const int g = gg & (N / 16 - 1); float2* z = z0 + (gg / (N / 16)) * N; const int jp = g & (Q2 - 1), base = ((g >> lq2) << (lq2 + 4)) + jp; float2 x[4][4];
; #pragma unroll
;     for (int q1 = 0; q1 < 4; ++q1)
; #pragma unroll
;       for (int q2 = 0; q2 < 4; ++q2) x[q1][q2] = z[base + q1 * Q1 + q2 * Q2];
; #pragma unroll
;     for (int q2 = 0; q2 < 4; ++q2) bfly_fwd(x[0][q2], x[1][q2], x[2][q2], x[3][q2], (float)(jp + q2 * Q2) * invM1, x[0][q2], x[1][q2], x[2][q2], x[3][q2]);
; #pragma unroll
;     for (int q1 = 0; q1 < 4; ++q1) bfly_fwd(x[q1][0], x[q1][1], x[q1][2], x[q1][3], (float)jp * invM2, x[q1][0], x[q1][1], x[q1][2], x[q1][3]);
.LBB0_1516:
	s_or_b64 exec, exec, s[0:1]
	s_add_i32 s0, 16, 0x20000
	v_mov_b32_e32 v0, s0
	v_readlane_b32 s0, v240, 48
	s_or_b32 s96, s21, s75
	s_waitcnt lgkmcnt(0)
	s_barrier
	ds_read_b128 v[6:9], v0
	v_mov_b32_e32 v0, s0
	s_lshl_b64 s[0:1], s[96:97], 2
	s_add_u32 s0, s18, s0
	s_addc_u32 s1, s19, s1
	ds_read_b128 v[2:5], v0
	global_load_dword v0, v1, s[0:1]
	s_movk_i32 s0, 0x400
	v_cmp_gt_i32_e32 vcc, s0, v10
	v_lshlrev_b32_e32 v11, 4, v10
	s_and_saveexec_b64 s[0:1], vcc
	s_cbranch_execz .LBB0_1519
	s_movk_i32 s10, 0x100
	s_movk_i32 s10, 0x200
	s_movk_i32 s10, 0x300
	v_lshlrev_b32_e32 v72, 4, v10
	s_mov_b64 s[12:13], 0
	v_mov_b32_e32 v73, v10
	v_and_b32_e32 v241, 0xff, v73
	v_cvt_f32_u32_e32 v250, v241
	v_mul_f32_e32 v250, 0x39800000, v250
	v_cos_f32_e32 v218, v250
	v_sin_f32_e32 v219, v250
	s_nop 1
	v_xor_b32_e32 v219, 0x80000000, v219
	s_nop 0
	v_pk_mul_f32 v[128:129], v[218:219], v[218:219] op_sel:[1,1] op_sel_hi:[1,0]
	s_nop 0
	v_pk_fma_f32 v[220:221], v[218:219], v[218:219], v[128:129] op_sel_hi:[0,1,1] neg_lo:[0,0,1]
	s_nop 0
	v_pk_mul_f32 v[128:129], v[220:221], v[218:219] op_sel:[1,1] op_sel_hi:[1,0]
	s_nop 0
	v_pk_fma_f32 v[222:223], v[220:221], v[218:219], v[128:129] op_sel_hi:[0,1,1] neg_lo:[0,0,1]
	v_pk_mul_f32 v[128:129], v[220:221], v[220:221] op_sel:[1,1] op_sel_hi:[1,0]
	s_nop 0
	v_pk_fma_f32 v[244:245], v[220:221], v[220:221], v[128:129] op_sel_hi:[0,1,1] neg_lo:[0,0,1]
	s_nop 0
	v_mul_f32_e32 v241, 0x3ec3ef15, v219
	v_mul_f32_e32 v250, 0xbec3ef15, v218
	v_fmamk_f32 v224, v218, 0x3f6c835e, v241
	v_fmamk_f32 v225, v219, 0x3f6c835e, v250
	v_mul_f32_e32 v241, 0x3f3504f3, v219
	v_mul_f32_e32 v250, 0xbf3504f3, v218
	v_fmamk_f32 v230, v218, 0x3f3504f3, v241
	v_fmamk_f32 v231, v219, 0x3f3504f3, v250
	v_mul_f32_e32 v241, 0x3f6c835e, v219
	v_mul_f32_e32 v250, 0xbf6c835e, v218
	v_fmamk_f32 v236, v218, 0x3ec3ef15, v241
	v_fmamk_f32 v237, v219, 0x3ec3ef15, v250
	v_mul_f32_e32 v241, 0x3f3504f3, v221
	v_mul_f32_e32 v250, 0xbf3504f3, v220
	v_fmamk_f32 v226, v220, 0x3f3504f3, v241
	v_fmamk_f32 v227, v221, 0x3f3504f3, v250
	v_mul_f32_e32 v241, 0x3f800000, v221
	v_mul_f32_e32 v250, 0xbf800000, v220
	v_fmamk_f32 v232, v220, 0x00000000, v241
	v_fmamk_f32 v233, v221, 0x00000000, v250
	v_mul_f32_e32 v241, 0x3f3504f3, v221
	v_mul_f32_e32 v250, 0xbf3504f3, v220
	v_fmamk_f32 v238, v220, 0xbf3504f3, v241
	v_fmamk_f32 v239, v221, 0xbf3504f3, v250
	v_mul_f32_e32 v241, 0x3f6c835e, v223
	v_mul_f32_e32 v250, 0xbf6c835e, v222
	v_fmamk_f32 v228, v222, 0x3ec3ef15, v241
	v_fmamk_f32 v229, v223, 0x3ec3ef15, v250
	v_mul_f32_e32 v241, 0x3f3504f3, v223
	v_mul_f32_e32 v250, 0xbf3504f3, v222
	v_fmamk_f32 v234, v222, 0xbf3504f3, v241
	v_fmamk_f32 v235, v223, 0xbf3504f3, v250
	v_mul_f32_e32 v241, 0xbec3ef15, v223
	v_mul_f32_e32 v250, 0x3ec3ef15, v222
	v_fmamk_f32 v242, v222, 0xbf6c835e, v241
	v_fmamk_f32 v243, v223, 0xbf6c835e, v250
	v_pk_mul_f32 v[128:129], v[244:245], v[244:245] op_sel:[1,1] op_sel_hi:[1,0]
	s_nop 0
	v_pk_fma_f32 v[246:247], v[244:245], v[244:245], v[128:129] op_sel_hi:[0,1,1] neg_lo:[0,0,1]
	s_nop 0
	v_pk_mul_f32 v[128:129], v[246:247], v[244:245] op_sel:[1,1] op_sel_hi:[1,0]
	s_nop 0
	v_pk_fma_f32 v[248:249], v[246:247], v[244:245], v[128:129] op_sel_hi:[0,1,1] neg_lo:[0,0,1]
	s_nop 0

; DI float2 twid(float r) { return float2{__builtin_amdgcn_cosf(r), -__builtin_amdgcn_sinf(r)}; }
; DI void bfly_fwd(float2 a0, float2 a1, float2 a2, float2 a3, float r, float2& o0, float2& o1, float2& o2, float2& o3) {
;   float2 t0 = {a0.x + a2.x, a0.y + a2.y}, t1 = {a0.x - a2.x, a0.y - a2.y}, t2 = {a1.x + a3.x, a1.y + a3.y}, t3 = {a1.x - a3.x, a1.y - a3.y};
;   float2 b0 = {t0.x + t2.x, t0.y + t2.y}, b2 = {t0.x - t2.x, t0.y - t2.y}, b1 = {t1.x + t3.y, t1.y - t3.x}, b3 = {t1.x - t3.y, t1.y + t3.x};
;   float2 w1 = twid(r), w2 = cmul(w1, w1), w3 = cmul(w2, w1);
;   o0 = b0; o1 = cmul(b1, w1); o2 = cmul(b2, w2); o3 = cmul(b3, w3);
; }
;   const int lq2 = lq1 - 2, Q1 = 1 << lq1, Q2 = 1 << lq2; const float invM1 = 1.f / (float)(4 << lq1), invM2 = 1.f / (float)(4 << lq2);
;   for (int gg = tid; gg < NBT * (N / 16); gg += NTHR) { const int g = gg & (N / 16 - 1); float2* z = z0 + (gg / (N / 16)) * N; const int jp = g & (Q2 - 1), base = ((g >> lq2) << (lq2 + 4)) + jp; float2 x[4][4];
; #pragma unroll
;     for (int q1 = 0; q1 < 4; ++q1)
; #pragma unroll
;       for (int q2 = 0; q2 < 4; ++q2) x[q1][q2] = z[base + q1 * Q1 + q2 * Q2];
; #pragma unroll
;     for (int q2 = 0; q2 < 4; ++q2) bfly_fwd(x[0][q2], x[1][q2], x[2][q2], x[3][q2], (float)(jp + q2 * Q2) * invM1, x[0][q2], x[1][q2], x[2][q2], x[3][q2]);
; #pragma unroll
;     for (int q1 = 0; q1 < 4; ++q1) bfly_fwd(x[q1][0], x[q1][1], x[q1][2], x[q1][3], (float)jp * invM2, x[q1][0], x[q1][1], x[q1][2], x[q1][3]);
.LBB0_1519:
	s_or_b64 exec, exec, s[0:1]
	s_waitcnt lgkmcnt(0)
	s_barrier
	s_and_saveexec_b64 s[0:1], vcc
	s_cbranch_execz .LBB0_1522
	v_and_b32_e32 v72, 15, v10
	s_mov_b64 s[10:11], 0
	v_mov_b32_e32 v73, v10
	v_and_b32_e32 v241, 0xf, v73
	v_cvt_f32_u32_e32 v250, v241
	v_mul_f32_e32 v250, 0x3b800000, v250
	v_cos_f32_e32 v218, v250
	v_sin_f32_e32 v219, v250
	s_nop 1
	v_xor_b32_e32 v219, 0x80000000, v219
	s_nop 0
	v_pk_mul_f32 v[128:129], v[218:219], v[218:219] op_sel:[1,1] op_sel_hi:[1,0]
	s_nop 0
	v_pk_fma_f32 v[220:221], v[218:219], v[218:219], v[128:129] op_sel_hi:[0,1,1] neg_lo:[0,0,1]
	s_nop 0
	v_pk_mul_f32 v[128:129], v[220:221], v[218:219] op_sel:[1,1] op_sel_hi:[1,0]
	s_nop 0
	v_pk_fma_f32 v[222:223], v[220:221], v[218:219], v[128:129] op_sel_hi:[0,1,1] neg_lo:[0,0,1]
	v_pk_mul_f32 v[128:129], v[220:221], v[220:221] op_sel:[1,1] op_sel_hi:[1,0]
	s_nop 0
	v_pk_fma_f32 v[244:245], v[220:221], v[220:221], v[128:129] op_sel_hi:[0,1,1] neg_lo:[0,0,1]
	s_nop 0
	v_mul_f32_e32 v241, 0x3ec3ef15, v219
	v_mul_f32_e32 v250, 0xbec3ef15, v218
	v_fmamk_f32 v224, v218, 0x3f6c835e, v241
	v_fmamk_f32 v225, v219, 0x3f6c835e, v250
	v_mul_f32_e32 v241, 0x3f3504f3, v219
	v_mul_f32_e32 v250, 0xbf3504f3, v218
	v_fmamk_f32 v230, v218, 0x3f3504f3, v241
	v_fmamk_f32 v231, v219, 0x3f3504f3, v250
	v_mul_f32_e32 v241, 0x3f6c835e, v219
	v_mul_f32_e32 v250, 0xbf6c835e, v218
	v_fmamk_f32 v236, v218, 0x3ec3ef15, v241
	v_fmamk_f32 v237, v219, 0x3ec3ef15, v250
	v_mul_f32_e32 v241, 0x3f3504f3, v221
	v_mul_f32_e32 v250, 0xbf3504f3, v220
	v_fmamk_f32 v226, v220, 0x3f3504f3, v241
	v_fmamk_f32 v227, v221, 0x3f3504f3, v250
	v_mul_f32_e32 v241, 0x3f800000, v221
	v_mul_f32_e32 v250, 0xbf800000, v220
	v_fmamk_f32 v232, v220, 0x00000000, v241
	v_fmamk_f32 v233, v221, 0x00000000, v250
	v_mul_f32_e32 v241, 0x3f3504f3, v221
	v_mul_f32_e32 v250, 0xbf3504f3, v220
	v_fmamk_f32 v238, v220, 0xbf3504f3, v241
	v_fmamk_f32 v239, v221, 0xbf3504f3, v250
	v_mul_f32_e32 v241, 0x3f6c835e, v223
	v_mul_f32_e32 v250, 0xbf6c835e, v222
	v_fmamk_f32 v228, v222, 0x3ec3ef15, v241
	v_fmamk_f32 v229, v223, 0x3ec3ef15, v250
	v_mul_f32_e32 v241, 0x3f3504f3, v223
	v_mul_f32_e32 v250, 0xbf3504f3, v222
	v_fmamk_f32 v234, v222, 0xbf3504f3, v241
	v_fmamk_f32 v235, v223, 0xbf3504f3, v250
	v_mul_f32_e32 v241, 0xbec3ef15, v223
	v_mul_f32_e32 v250, 0x3ec3ef15, v222
	v_fmamk_f32 v242, v222, 0xbf6c835e, v241
	v_fmamk_f32 v243, v223, 0xbf6c835e, v250
	v_pk_mul_f32 v[128:129], v[244:245], v[244:245] op_sel:[1,1] op_sel_hi:[1,0]
	s_nop 0
	v_pk_fma_f32 v[246:247], v[244:245], v[244:245], v[128:129] op_sel_hi:[0,1,1] neg_lo:[0,0,1]
	s_nop 0
	v_pk_mul_f32 v[128:129], v[246:247], v[244:245] op_sel:[1,1] op_sel_hi:[1,0]
	s_nop 0
	v_pk_fma_f32 v[248:249], v[246:247], v[244:245], v[128:129] op_sel_hi:[0,1,1] neg_lo:[0,0,1]
	s_nop 0

; DI float2 twid(float r) { return float2{__builtin_amdgcn_cosf(r), -__builtin_amdgcn_sinf(r)}; }
; DI void bfly_fwd(float2 a0, float2 a1, float2 a2, float2 a3, float r, float2& o0, float2& o1, float2& o2, float2& o3) {
;   float2 t0 = {a0.x + a2.x, a0.y + a2.y}, t1 = {a0.x - a2.x, a0.y - a2.y}, t2 = {a1.x + a3.x, a1.y + a3.y}, t3 = {a1.x - a3.x, a1.y - a3.y};
;   float2 b0 = {t0.x + t2.x, t0.y + t2.y}, b2 = {t0.x - t2.x, t0.y - t2.y}, b1 = {t1.x + t3.y, t1.y - t3.x}, b3 = {t1.x - t3.y, t1.y + t3.x};
;   float2 w1 = twid(r), w2 = cmul(w1, w1), w3 = cmul(w2, w1);
;   o0 = b0; o1 = cmul(b1, w1); o2 = cmul(b2, w2); o3 = cmul(b3, w3);
; }
;   const int lq2 = lq1 - 2, Q1 = 1 << lq1, Q2 = 1 << lq2; const float invM1 = 1.f / (float)(4 << lq1), invM2 = 1.f / (float)(4 << lq2);
;   for (int gg = tid; gg < NBT * (N / 16); gg += NTHR) { const int g = gg & (N / 16 - 1); float2* z = z0 + (gg / (N / 16)) * N; const int jp = g & (Q2 - 1), base = ((g >> lq2) << (lq2 + 4)) + jp; float2 x[4][4];
; #pragma unroll
;     for (int q1 = 0; q1 < 4; ++q1)
; #pragma unroll
;       for (int q2 = 0; q2 < 4; ++q2) x[q1][q2] = z[base + q1 * Q1 + q2 * Q2];
; #pragma unroll
;     for (int q2 = 0; q2 < 4; ++q2) bfly_fwd(x[0][q2], x[1][q2], x[2][q2], x[3][q2], (float)(jp + q2 * Q2) * invM1, x[0][q2], x[1][q2], x[2][q2], x[3][q2]);
; #pragma unroll
;     for (int q1 = 0; q1 < 4; ++q1) bfly_fwd(x[q1][0], x[q1][1], x[q1][2], x[q1][3], (float)jp * invM2, x[q1][0], x[q1][1], x[q1][2], x[q1][3]);
.LBB0_1598:
	s_or_b64 exec, exec, s[0:1]
	s_movk_i32 s0, 0x400
	v_cmp_gt_i32_e32 vcc, s0, v75
	s_movk_i32 s0, 0x100
	v_or_b32_sdwa v77, v75, s0 dst_sel:DWORD dst_unused:UNUSED_PAD src0_sel:BYTE_0 src1_sel:DWORD
	s_movk_i32 s0, 0x200
	v_lshlrev_b32_e32 v62, 7, v75
	v_cvt_f32_ubyte0_e32 v2, v75
	v_or_b32_sdwa v76, v75, s0 dst_sel:DWORD dst_unused:UNUSED_PAD src0_sel:BYTE_0 src1_sel:DWORD
	s_movk_i32 s0, 0x300
	v_and_b32_e32 v79, 0x8000, v62
	v_lshlrev_b32_sdwa v80, v151, v75 dst_sel:DWORD dst_unused:UNUSED_PAD src0_sel:DWORD src1_sel:BYTE_0
	v_mul_f32_e32 v78, 0x39800000, v2
	v_or_b32_sdwa v0, v75, s0 dst_sel:DWORD dst_unused:UNUSED_PAD src0_sel:BYTE_0 src1_sel:DWORD
	v_mul_f32_e32 v81, 0x3a800000, v2
	s_waitcnt lgkmcnt(0)
	s_barrier
	s_and_saveexec_b64 s[0:1], vcc
	s_cbranch_execz .LBB0_1601
	v_add3_u32 v63, 16, v79, v80
	s_mov_b64 s[80:81], 0
	v_mov_b32_e32 v64, v75
	v_and_b32_e32 v241, 0xff, v64
	v_cvt_f32_u32_e32 v250, v241
	v_mul_f32_e32 v250, 0x39800000, v250
	v_cos_f32_e32 v218, v250
	v_sin_f32_e32 v219, v250
	s_nop 1
	v_xor_b32_e32 v219, 0x80000000, v219
	s_nop 0
	v_pk_mul_f32 v[122:123], v[218:219], v[218:219] op_sel:[1,1] op_sel_hi:[1,0]
	s_nop 0
	v_pk_fma_f32 v[220:221], v[218:219], v[218:219], v[122:123] op_sel_hi:[0,1,1] neg_lo:[0,0,1]
	s_nop 0
	v_pk_mul_f32 v[122:123], v[220:221], v[218:219] op_sel:[1,1] op_sel_hi:[1,0]
	s_nop 0
	v_pk_fma_f32 v[222:223], v[220:221], v[218:219], v[122:123] op_sel_hi:[0,1,1] neg_lo:[0,0,1]
	v_pk_mul_f32 v[122:123], v[220:221], v[220:221] op_sel:[1,1] op_sel_hi:[1,0]
	s_nop 0
	v_pk_fma_f32 v[244:245], v[220:221], v[220:221], v[122:123] op_sel_hi:[0,1,1] neg_lo:[0,0,1]
	s_nop 0
	v_mul_f32_e32 v241, 0x3ec3ef15, v219
	v_mul_f32_e32 v250, 0xbec3ef15, v218
	v_fmamk_f32 v224, v218, 0x3f6c835e, v241
	v_fmamk_f32 v225, v219, 0x3f6c835e, v250
	v_mul_f32_e32 v241, 0x3f3504f3, v219
	v_mul_f32_e32 v250, 0xbf3504f3, v218
	v_fmamk_f32 v230, v218, 0x3f3504f3, v241
	v_fmamk_f32 v231, v219, 0x3f3504f3, v250
	v_mul_f32_e32 v241, 0x3f6c835e, v219
	v_mul_f32_e32 v250, 0xbf6c835e, v218
	v_fmamk_f32 v236, v218, 0x3ec3ef15, v241
	v_fmamk_f32 v237, v219, 0x3ec3ef15, v250
	v_mul_f32_e32 v241, 0x3f3504f3, v221
	v_mul_f32_e32 v250, 0xbf3504f3, v220
	v_fmamk_f32 v226, v220, 0x3f3504f3, v241
	v_fmamk_f32 v227, v221, 0x3f3504f3, v250
	v_mul_f32_e32 v241, 0x3f800000, v221
	v_mul_f32_e32 v250, 0xbf800000, v220
	v_fmamk_f32 v232, v220, 0x00000000, v241
	v_fmamk_f32 v233, v221, 0x00000000, v250
	v_mul_f32_e32 v241, 0x3f3504f3, v221
	v_mul_f32_e32 v250, 0xbf3504f3, v220
	v_fmamk_f32 v238, v220, 0xbf3504f3, v241
	v_fmamk_f32 v239, v221, 0xbf3504f3, v250
	v_mul_f32_e32 v241, 0x3f6c835e, v223
	v_mul_f32_e32 v250, 0xbf6c835e, v222
	v_fmamk_f32 v228, v222, 0x3ec3ef15, v241
	v_fmamk_f32 v229, v223, 0x3ec3ef15, v250
	v_mul_f32_e32 v241, 0x3f3504f3, v223
	v_mul_f32_e32 v250, 0xbf3504f3, v222
	v_fmamk_f32 v234, v222, 0xbf3504f3, v241
	v_fmamk_f32 v235, v223, 0xbf3504f3, v250
	v_mul_f32_e32 v241, 0xbec3ef15, v223
	v_mul_f32_e32 v250, 0x3ec3ef15, v222
	v_fmamk_f32 v242, v222, 0xbf6c835e, v241
	v_fmamk_f32 v243, v223, 0xbf6c835e, v250
	v_pk_mul_f32 v[122:123], v[244:245], v[244:245] op_sel:[1,1] op_sel_hi:[1,0]
	s_nop 0
	v_pk_fma_f32 v[246:247], v[244:245], v[244:245], v[122:123] op_sel_hi:[0,1,1] neg_lo:[0,0,1]
	s_nop 0
	v_pk_mul_f32 v[122:123], v[246:247], v[244:245] op_sel:[1,1] op_sel_hi:[1,0]
	s_nop 0
	v_pk_fma_f32 v[248:249], v[246:247], v[244:245], v[122:123] op_sel_hi:[0,1,1] neg_lo:[0,0,1]
	s_nop 0

; DI float2 twid(float r) { return float2{__builtin_amdgcn_cosf(r), -__builtin_amdgcn_sinf(r)}; }
; DI void bfly_fwd(float2 a0, float2 a1, float2 a2, float2 a3, float r, float2& o0, float2& o1, float2& o2, float2& o3) {
;   float2 t0 = {a0.x + a2.x, a0.y + a2.y}, t1 = {a0.x - a2.x, a0.y - a2.y}, t2 = {a1.x + a3.x, a1.y + a3.y}, t3 = {a1.x - a3.x, a1.y - a3.y};
;   float2 b0 = {t0.x + t2.x, t0.y + t2.y}, b2 = {t0.x - t2.x, t0.y - t2.y}, b1 = {t1.x + t3.y, t1.y - t3.x}, b3 = {t1.x - t3.y, t1.y + t3.x};
;   float2 w1 = twid(r), w2 = cmul(w1, w1), w3 = cmul(w2, w1);
;   o0 = b0; o1 = cmul(b1, w1); o2 = cmul(b2, w2); o3 = cmul(b3, w3);
; }
;   const int lq2 = lq1 - 2, Q1 = 1 << lq1, Q2 = 1 << lq2; const float invM1 = 1.f / (float)(4 << lq1), invM2 = 1.f / (float)(4 << lq2);
;   for (int gg = tid; gg < NBT * (N / 16); gg += NTHR) { const int g = gg & (N / 16 - 1); float2* z = z0 + (gg / (N / 16)) * N; const int jp = g & (Q2 - 1), base = ((g >> lq2) << (lq2 + 4)) + jp; float2 x[4][4];
; #pragma unroll
;     for (int q1 = 0; q1 < 4; ++q1)
; #pragma unroll
;       for (int q2 = 0; q2 < 4; ++q2) x[q1][q2] = z[base + q1 * Q1 + q2 * Q2];
; #pragma unroll
;     for (int q2 = 0; q2 < 4; ++q2) bfly_fwd(x[0][q2], x[1][q2], x[2][q2], x[3][q2], (float)(jp + q2 * Q2) * invM1, x[0][q2], x[1][q2], x[2][q2], x[3][q2]);
; #pragma unroll
;     for (int q1 = 0; q1 < 4; ++q1) bfly_fwd(x[q1][0], x[q1][1], x[q1][2], x[q1][3], (float)jp * invM2, x[q1][0], x[q1][1], x[q1][2], x[q1][3]);
.LBB0_1601:
	s_or_b64 exec, exec, s[0:1]
	v_and_b32_e32 v2, 15, v75
	v_and_b32_e32 v66, 0xf800, v62
	v_lshlrev_b32_e32 v67, 3, v2
	v_cvt_f32_ubyte0_e32 v65, v2
	v_or_b32_e32 v64, 16, v2
	v_or_b32_e32 v63, 32, v2
	v_or_b32_e32 v62, 48, v2
	s_waitcnt lgkmcnt(0)
	s_barrier
	s_and_saveexec_b64 s[0:1], vcc
	s_cbranch_execz .LBB0_1604
	v_add3_u32 v68, 16, v66, v67
	s_mov_b64 s[80:81], 0
	v_mov_b32_e32 v69, v75
	v_and_b32_e32 v241, 0xf, v69
	v_cvt_f32_u32_e32 v250, v241
	v_mul_f32_e32 v250, 0x3b800000, v250
	v_cos_f32_e32 v218, v250
	v_sin_f32_e32 v219, v250
	s_nop 1
	v_xor_b32_e32 v219, 0x80000000, v219
	s_nop 0
	v_pk_mul_f32 v[128:129], v[218:219], v[218:219] op_sel:[1,1] op_sel_hi:[1,0]
	s_nop 0
	v_pk_fma_f32 v[220:221], v[218:219], v[218:219], v[128:129] op_sel_hi:[0,1,1] neg_lo:[0,0,1]
	s_nop 0
	v_pk_mul_f32 v[128:129], v[220:221], v[218:219] op_sel:[1,1] op_sel_hi:[1,0]
	s_nop 0
	v_pk_fma_f32 v[222:223], v[220:221], v[218:219], v[128:129] op_sel_hi:[0,1,1] neg_lo:[0,0,1]
	v_pk_mul_f32 v[128:129], v[220:221], v[220:221] op_sel:[1,1] op_sel_hi:[1,0]
	s_nop 0
	v_pk_fma_f32 v[244:245], v[220:221], v[220:221], v[128:129] op_sel_hi:[0,1,1] neg_lo:[0,0,1]
	s_nop 0
	v_mul_f32_e32 v241, 0x3ec3ef15, v219
	v_mul_f32_e32 v250, 0xbec3ef15, v218
	v_fmamk_f32 v224, v218, 0x3f6c835e, v241
	v_fmamk_f32 v225, v219, 0x3f6c835e, v250
	v_mul_f32_e32 v241, 0x3f3504f3, v219
	v_mul_f32_e32 v250, 0xbf3504f3, v218
	v_fmamk_f32 v230, v218, 0x3f3504f3, v241
	v_fmamk_f32 v231, v219, 0x3f3504f3, v250
	v_mul_f32_e32 v241, 0x3f6c835e, v219
	v_mul_f32_e32 v250, 0xbf6c835e, v218
	v_fmamk_f32 v236, v218, 0x3ec3ef15, v241
	v_fmamk_f32 v237, v219, 0x3ec3ef15, v250
	v_mul_f32_e32 v241, 0x3f3504f3, v221
	v_mul_f32_e32 v250, 0xbf3504f3, v220
	v_fmamk_f32 v226, v220, 0x3f3504f3, v241
	v_fmamk_f32 v227, v221, 0x3f3504f3, v250
	v_mul_f32_e32 v241, 0x3f800000, v221
	v_mul_f32_e32 v250, 0xbf800000, v220
	v_fmamk_f32 v232, v220, 0x00000000, v241
	v_fmamk_f32 v233, v221, 0x00000000, v250
	v_mul_f32_e32 v241, 0x3f3504f3, v221
	v_mul_f32_e32 v250, 0xbf3504f3, v220
	v_fmamk_f32 v238, v220, 0xbf3504f3, v241
	v_fmamk_f32 v239, v221, 0xbf3504f3, v250
	v_mul_f32_e32 v241, 0x3f6c835e, v223
	v_mul_f32_e32 v250, 0xbf6c835e, v222
	v_fmamk_f32 v228, v222, 0x3ec3ef15, v241
	v_fmamk_f32 v229, v223, 0x3ec3ef15, v250
	v_mul_f32_e32 v241, 0x3f3504f3, v223
	v_mul_f32_e32 v250, 0xbf3504f3, v222
	v_fmamk_f32 v234, v222, 0xbf3504f3, v241
	v_fmamk_f32 v235, v223, 0xbf3504f3, v250
	v_mul_f32_e32 v241, 0xbec3ef15, v223
	v_mul_f32_e32 v250, 0x3ec3ef15, v222
	v_fmamk_f32 v242, v222, 0xbf6c835e, v241
	v_fmamk_f32 v243, v223, 0xbf6c835e, v250
	v_pk_mul_f32 v[128:129], v[244:245], v[244:245] op_sel:[1,1] op_sel_hi:[1,0]
	s_nop 0
	v_pk_fma_f32 v[246:247], v[244:245], v[244:245], v[128:129] op_sel_hi:[0,1,1] neg_lo:[0,0,1]
	s_nop 0
	v_pk_mul_f32 v[128:129], v[246:247], v[244:245] op_sel:[1,1] op_sel_hi:[1,0]
	s_nop 0
	v_pk_fma_f32 v[248:249], v[246:247], v[244:245], v[128:129] op_sel_hi:[0,1,1] neg_lo:[0,0,1]
	s_nop 0

; DI float2 twid(float r) { return float2{__builtin_amdgcn_cosf(r), -__builtin_amdgcn_sinf(r)}; }
; DI void bfly_inv(float2 s0, float2 s1, float2 s2, float2 s3, float r, float2& o0, float2& o1, float2& o2, float2& o3) {
;   float2 w1 = twid(r), w2 = cmul(w1, w1), w3 = cmul(w2, w1);
;   float2 c0 = s0, c1 = cmulc(s1, w1), c2 = cmulc(s2, w2), c3 = cmulc(s3, w3);
;   const int lq1 = lq2 + 2, Q1 = 1 << lq1, Q2 = 1 << lq2; const float invM1 = 1.f / (float)(4 << lq1), invM2 = 1.f / (float)(4 << lq2);
;   for (int gg = tid; gg < NBT * (N / 16); gg += NTHR) { const int g = gg & (N / 16 - 1); float2* z = z0 + (gg / (N / 16)) * N; const int jp = g & (Q2 - 1), base = ((g >> lq2) << (lq2 + 4)) + jp; float2 x[4][4];
; #pragma unroll
;     for (int q1 = 0; q1 < 4; ++q1)
; #pragma unroll
;       for (int q2 = 0; q2 < 4; ++q2) x[q1][q2] = z[base + q1 * Q1 + q2 * Q2];
; #pragma unroll
;     for (int q1 = 0; q1 < 4; ++q1) bfly_inv(x[q1][0], x[q1][1], x[q1][2], x[q1][3], (float)jp * invM2, x[q1][0], x[q1][1], x[q1][2], x[q1][3]);
; #pragma unroll
;     for (int q2 = 0; q2 < 4; ++q2) bfly_inv(x[0][q2], x[1][q2], x[2][q2], x[3][q2], (float)(jp + q2 * Q2) * invM1, x[0][q2], x[1][q2], x[2][q2], x[3][q2]);
.LBB0_1616:
	s_or_b64 exec, exec, s[0:1]
	s_waitcnt lgkmcnt(0)
	s_barrier
	s_and_saveexec_b64 s[0:1], vcc
	s_cbranch_execz .LBB0_1619
	v_add3_u32 v20, 16, v66, v67
	s_mov_b64 s[80:81], 0
	v_mov_b32_e32 v82, v75
	v_and_b32_e32 v241, 0xf, v82
	v_cvt_f32_u32_e32 v250, v241
	v_mul_f32_e32 v250, 0x3b800000, v250
	v_cos_f32_e32 v218, v250
	v_sin_f32_e32 v219, v250
	s_nop 1
	s_nop 0
	v_pk_mul_f32 v[132:133], v[218:219], v[218:219] op_sel:[1,1] op_sel_hi:[1,0]
	s_nop 0
	v_pk_fma_f32 v[220:221], v[218:219], v[218:219], v[132:133] op_sel_hi:[0,1,1] neg_lo:[0,0,1]
	s_nop 0
	v_pk_mul_f32 v[132:133], v[220:221], v[218:219] op_sel:[1,1] op_sel_hi:[1,0]
	s_nop 0
	v_pk_fma_f32 v[222:223], v[220:221], v[218:219], v[132:133] op_sel_hi:[0,1,1] neg_lo:[0,0,1]
	v_pk_mul_f32 v[132:133], v[220:221], v[220:221] op_sel:[1,1] op_sel_hi:[1,0]
	s_nop 0
	v_pk_fma_f32 v[244:245], v[220:221], v[220:221], v[132:133] op_sel_hi:[0,1,1] neg_lo:[0,0,1]
	s_nop 0
	v_mul_f32_e32 v241, 0xbec3ef15, v219
	v_mul_f32_e32 v250, 0x3ec3ef15, v218
	v_fmamk_f32 v224, v218, 0x3f6c835e, v241
	v_fmamk_f32 v225, v219, 0x3f6c835e, v250
	v_mul_f32_e32 v241, 0xbf3504f3, v219
	v_mul_f32_e32 v250, 0x3f3504f3, v218
	v_fmamk_f32 v230, v218, 0x3f3504f3, v241
	v_fmamk_f32 v231, v219, 0x3f3504f3, v250
	v_mul_f32_e32 v241, 0xbf6c835e, v219
	v_mul_f32_e32 v250, 0x3f6c835e, v218
	v_fmamk_f32 v236, v218, 0x3ec3ef15, v241
	v_fmamk_f32 v237, v219, 0x3ec3ef15, v250
	v_mul_f32_e32 v241, 0xbf3504f3, v221
	v_mul_f32_e32 v250, 0x3f3504f3, v220
	v_fmamk_f32 v226, v220, 0x3f3504f3, v241
	v_fmamk_f32 v227, v221, 0x3f3504f3, v250
	v_mul_f32_e32 v241, 0xbf800000, v221
	v_mul_f32_e32 v250, 0x3f800000, v220
	v_fmamk_f32 v232, v220, 0x00000000, v241
	v_fmamk_f32 v233, v221, 0x00000000, v250
	v_mul_f32_e32 v241, 0xbf3504f3, v221
	v_mul_f32_e32 v250, 0x3f3504f3, v220
	v_fmamk_f32 v238, v220, 0xbf3504f3, v241
	v_fmamk_f32 v239, v221, 0xbf3504f3, v250
	v_mul_f32_e32 v241, 0xbf6c835e, v223
	v_mul_f32_e32 v250, 0x3f6c835e, v222
	v_fmamk_f32 v228, v222, 0x3ec3ef15, v241
	v_fmamk_f32 v229, v223, 0x3ec3ef15, v250
	v_mul_f32_e32 v241, 0xbf3504f3, v223
	v_mul_f32_e32 v250, 0x3f3504f3, v222
	v_fmamk_f32 v234, v222, 0xbf3504f3, v241
	v_fmamk_f32 v235, v223, 0xbf3504f3, v250
	v_mul_f32_e32 v241, 0x3ec3ef15, v223
	v_mul_f32_e32 v250, 0xbec3ef15, v222
	v_fmamk_f32 v242, v222, 0xbf6c835e, v241
	v_fmamk_f32 v243, v223, 0xbf6c835e, v250
	v_pk_mul_f32 v[132:133], v[244:245], v[244:245] op_sel:[1,1] op_sel_hi:[1,0]
	s_nop 0
	v_pk_fma_f32 v[246:247], v[244:245], v[244:245], v[132:133] op_sel_hi:[0,1,1] neg_lo:[0,0,1]
	s_nop 0
	v_pk_mul_f32 v[132:133], v[246:247], v[244:245] op_sel:[1,1] op_sel_hi:[1,0]
	s_nop 0
	v_pk_fma_f32 v[248:249], v[246:247], v[244:245], v[132:133] op_sel_hi:[0,1,1] neg_lo:[0,0,1]
	s_nop 0

; DI float2 twid(float r) { return float2{__builtin_amdgcn_cosf(r), -__builtin_amdgcn_sinf(r)}; }
; DI void bfly_inv(float2 s0, float2 s1, float2 s2, float2 s3, float r, float2& o0, float2& o1, float2& o2, float2& o3) {
;   float2 w1 = twid(r), w2 = cmul(w1, w1), w3 = cmul(w2, w1);
;   float2 c0 = s0, c1 = cmulc(s1, w1), c2 = cmulc(s2, w2), c3 = cmulc(s3, w3);
;   const int lq1 = lq2 + 2, Q1 = 1 << lq1, Q2 = 1 << lq2; const float invM1 = 1.f / (float)(4 << lq1), invM2 = 1.f / (float)(4 << lq2);
;   for (int gg = tid; gg < NBT * (N / 16); gg += NTHR) { const int g = gg & (N / 16 - 1); float2* z = z0 + (gg / (N / 16)) * N; const int jp = g & (Q2 - 1), base = ((g >> lq2) << (lq2 + 4)) + jp; float2 x[4][4];
; #pragma unroll
;     for (int q1 = 0; q1 < 4; ++q1)
; #pragma unroll
;       for (int q2 = 0; q2 < 4; ++q2) x[q1][q2] = z[base + q1 * Q1 + q2 * Q2];
; #pragma unroll
;     for (int q1 = 0; q1 < 4; ++q1) bfly_inv(x[q1][0], x[q1][1], x[q1][2], x[q1][3], (float)jp * invM2, x[q1][0], x[q1][1], x[q1][2], x[q1][3]);
; #pragma unroll
;     for (int q2 = 0; q2 < 4; ++q2) bfly_inv(x[0][q2], x[1][q2], x[2][q2], x[3][q2], (float)(jp + q2 * Q2) * invM1, x[0][q2], x[1][q2], x[2][q2], x[3][q2]);
.LBB0_1619:
	s_or_b64 exec, exec, s[0:1]
	s_waitcnt lgkmcnt(0)
	s_barrier
	s_and_saveexec_b64 s[12:13], vcc
	s_cbranch_execz .LBB0_1622
	v_cvt_f32_u32_e32 v9, v76
	v_mul_f32_e32 v6, 0x39800000, v9
	v_sin_f32_e32 v33, v6
	v_cos_f32_e32 v35, v6
	v_mul_f32_e32 v6, v33, v33
	v_fma_f32 v36, v35, v35, -v6
	v_mul_f32_e32 v0, v33, v36
	v_add3_u32 v20, 16, v79, v80
	s_mov_b64 s[0:1], 0
	v_and_b32_e32 v241, 0xff, v75
	v_cvt_f32_u32_e32 v250, v241
	v_mul_f32_e32 v250, 0x39800000, v250
	v_cos_f32_e32 v218, v250
	v_sin_f32_e32 v219, v250
	s_nop 1
	s_nop 0
	v_pk_mul_f32 v[124:125], v[218:219], v[218:219] op_sel:[1,1] op_sel_hi:[1,0]
	s_nop 0
	v_pk_fma_f32 v[220:221], v[218:219], v[218:219], v[124:125] op_sel_hi:[0,1,1] neg_lo:[0,0,1]
	s_nop 0
	v_pk_mul_f32 v[124:125], v[220:221], v[218:219] op_sel:[1,1] op_sel_hi:[1,0]
	s_nop 0
	v_pk_fma_f32 v[222:223], v[220:221], v[218:219], v[124:125] op_sel_hi:[0,1,1] neg_lo:[0,0,1]
	v_pk_mul_f32 v[124:125], v[220:221], v[220:221] op_sel:[1,1] op_sel_hi:[1,0]
	s_nop 0
	v_pk_fma_f32 v[244:245], v[220:221], v[220:221], v[124:125] op_sel_hi:[0,1,1] neg_lo:[0,0,1]
	s_nop 0
	v_mul_f32_e32 v241, 0xbec3ef15, v219
	v_mul_f32_e32 v250, 0x3ec3ef15, v218
	v_fmamk_f32 v224, v218, 0x3f6c835e, v241
	v_fmamk_f32 v225, v219, 0x3f6c835e, v250
	v_mul_f32_e32 v241, 0xbf3504f3, v219
	v_mul_f32_e32 v250, 0x3f3504f3, v218
	v_fmamk_f32 v230, v218, 0x3f3504f3, v241
	v_fmamk_f32 v231, v219, 0x3f3504f3, v250
	v_mul_f32_e32 v241, 0xbf6c835e, v219
	v_mul_f32_e32 v250, 0x3f6c835e, v218
	v_fmamk_f32 v236, v218, 0x3ec3ef15, v241
	v_fmamk_f32 v237, v219, 0x3ec3ef15, v250
	v_mul_f32_e32 v241, 0xbf3504f3, v221
	v_mul_f32_e32 v250, 0x3f3504f3, v220
	v_fmamk_f32 v226, v220, 0x3f3504f3, v241
	v_fmamk_f32 v227, v221, 0x3f3504f3, v250
	v_mul_f32_e32 v241, 0xbf800000, v221
	v_mul_f32_e32 v250, 0x3f800000, v220
	v_fmamk_f32 v232, v220, 0x00000000, v241
	v_fmamk_f32 v233, v221, 0x00000000, v250
	v_mul_f32_e32 v241, 0xbf3504f3, v221
	v_mul_f32_e32 v250, 0x3f3504f3, v220
	v_fmamk_f32 v238, v220, 0xbf3504f3, v241
	v_fmamk_f32 v239, v221, 0xbf3504f3, v250
	v_mul_f32_e32 v241, 0xbf6c835e, v223
	v_mul_f32_e32 v250, 0x3f6c835e, v222
	v_fmamk_f32 v228, v222, 0x3ec3ef15, v241
	v_fmamk_f32 v229, v223, 0x3ec3ef15, v250
	v_mul_f32_e32 v241, 0xbf3504f3, v223
	v_mul_f32_e32 v250, 0x3f3504f3, v222
	v_fmamk_f32 v234, v222, 0xbf3504f3, v241
	v_fmamk_f32 v235, v223, 0xbf3504f3, v250
	v_mul_f32_e32 v241, 0x3ec3ef15, v223
	v_mul_f32_e32 v250, 0xbec3ef15, v222
	v_fmamk_f32 v242, v222, 0xbf6c835e, v241
	v_fmamk_f32 v243, v223, 0xbf6c835e, v250
	v_pk_mul_f32 v[124:125], v[244:245], v[244:245] op_sel:[1,1] op_sel_hi:[1,0]
	s_nop 0
	v_pk_fma_f32 v[246:247], v[244:245], v[244:245], v[124:125] op_sel_hi:[0,1,1] neg_lo:[0,0,1]
	s_nop 0
	v_pk_mul_f32 v[124:125], v[246:247], v[244:245] op_sel:[1,1] op_sel_hi:[1,0]
	s_nop 0
	v_pk_fma_f32 v[248:249], v[246:247], v[244:245], v[124:125] op_sel_hi:[0,1,1] neg_lo:[0,0,1]
	s_nop 0

; DI float2 twid(float r) { return float2{__builtin_amdgcn_cosf(r), -__builtin_amdgcn_sinf(r)}; }
; DI void bfly_fwd(float2 a0, float2 a1, float2 a2, float2 a3, float r, float2& o0, float2& o1, float2& o2, float2& o3) {
;   float2 t0 = {a0.x + a2.x, a0.y + a2.y}, t1 = {a0.x - a2.x, a0.y - a2.y}, t2 = {a1.x + a3.x, a1.y + a3.y}, t3 = {a1.x - a3.x, a1.y - a3.y};
;   float2 b0 = {t0.x + t2.x, t0.y + t2.y}, b2 = {t0.x - t2.x, t0.y - t2.y}, b1 = {t1.x + t3.y, t1.y - t3.x}, b3 = {t1.x - t3.y, t1.y + t3.x};
;   float2 w1 = twid(r), w2 = cmul(w1, w1), w3 = cmul(w2, w1);
;   o0 = b0; o1 = cmul(b1, w1); o2 = cmul(b2, w2); o3 = cmul(b3, w3);
; }
;   const int lq2 = lq1 - 2, Q1 = 1 << lq1, Q2 = 1 << lq2; const float invM1 = 1.f / (float)(4 << lq1), invM2 = 1.f / (float)(4 << lq2);
;   for (int gg = tid; gg < NBT * (N / 16); gg += NTHR) { const int g = gg & (N / 16 - 1); float2* z = z0 + (gg / (N / 16)) * N; const int jp = g & (Q2 - 1), base = ((g >> lq2) << (lq2 + 4)) + jp; float2 x[4][4];
; #pragma unroll
;     for (int q1 = 0; q1 < 4; ++q1)
; #pragma unroll
;       for (int q2 = 0; q2 < 4; ++q2) x[q1][q2] = z[base + q1 * Q1 + q2 * Q2];
; #pragma unroll
;     for (int q2 = 0; q2 < 4; ++q2) bfly_fwd(x[0][q2], x[1][q2], x[2][q2], x[3][q2], (float)(jp + q2 * Q2) * invM1, x[0][q2], x[1][q2], x[2][q2], x[3][q2]);
; #pragma unroll
;     for (int q1 = 0; q1 < 4; ++q1) bfly_fwd(x[q1][0], x[q1][1], x[q1][2], x[q1][3], (float)jp * invM2, x[q1][0], x[q1][1], x[q1][2], x[q1][3]);
.LBB0_1630:
	s_or_b64 exec, exec, s[0:1]
	s_movk_i32 s0, 0x400
	v_cmp_gt_i32_e32 vcc, s0, v76
	s_movk_i32 s0, 0x100
	v_or_b32_sdwa v80, v76, s0 dst_sel:DWORD dst_unused:UNUSED_PAD src0_sel:BYTE_0 src1_sel:DWORD
	s_movk_i32 s0, 0x200
	v_cvt_f32_ubyte0_e32 v4, v76
	v_or_b32_sdwa v79, v76, s0 dst_sel:DWORD dst_unused:UNUSED_PAD src0_sel:BYTE_0 src1_sel:DWORD
	s_movk_i32 s0, 0x300
	v_mul_f32_e32 v81, 0x39800000, v4
	v_or_b32_sdwa v78, v76, s0 dst_sel:DWORD dst_unused:UNUSED_PAD src0_sel:BYTE_0 src1_sel:DWORD
	v_mul_f32_e32 v82, 0x3a800000, v4
	v_lshlrev_b32_e32 v77, 4, v76
	s_waitcnt lgkmcnt(0)
	s_barrier
	s_and_saveexec_b64 s[0:1], vcc
	s_cbranch_execz .LBB0_1633
	v_lshlrev_b32_e32 v64, 4, v76
	s_mov_b64 s[14:15], 0
	v_mov_b32_e32 v65, v76
	v_and_b32_e32 v241, 0xff, v65
	v_cvt_f32_u32_e32 v250, v241
	v_mul_f32_e32 v250, 0x39800000, v250
	v_cos_f32_e32 v218, v250
	v_sin_f32_e32 v219, v250
	s_nop 1
	v_xor_b32_e32 v219, 0x80000000, v219
	s_nop 0
	v_pk_mul_f32 v[126:127], v[218:219], v[218:219] op_sel:[1,1] op_sel_hi:[1,0]
	s_nop 0
	v_pk_fma_f32 v[220:221], v[218:219], v[218:219], v[126:127] op_sel_hi:[0,1,1] neg_lo:[0,0,1]
	s_nop 0
	v_pk_mul_f32 v[126:127], v[220:221], v[218:219] op_sel:[1,1] op_sel_hi:[1,0]
	s_nop 0
	v_pk_fma_f32 v[222:223], v[220:221], v[218:219], v[126:127] op_sel_hi:[0,1,1] neg_lo:[0,0,1]
	v_pk_mul_f32 v[126:127], v[220:221], v[220:221] op_sel:[1,1] op_sel_hi:[1,0]
	s_nop 0
	v_pk_fma_f32 v[244:245], v[220:221], v[220:221], v[126:127] op_sel_hi:[0,1,1] neg_lo:[0,0,1]
	s_nop 0
	v_mul_f32_e32 v241, 0x3ec3ef15, v219
	v_mul_f32_e32 v250, 0xbec3ef15, v218
	v_fmamk_f32 v224, v218, 0x3f6c835e, v241
	v_fmamk_f32 v225, v219, 0x3f6c835e, v250
	v_mul_f32_e32 v241, 0x3f3504f3, v219
	v_mul_f32_e32 v250, 0xbf3504f3, v218
	v_fmamk_f32 v230, v218, 0x3f3504f3, v241
	v_fmamk_f32 v231, v219, 0x3f3504f3, v250
	v_mul_f32_e32 v241, 0x3f6c835e, v219
	v_mul_f32_e32 v250, 0xbf6c835e, v218
	v_fmamk_f32 v236, v218, 0x3ec3ef15, v241
	v_fmamk_f32 v237, v219, 0x3ec3ef15, v250
	v_mul_f32_e32 v241, 0x3f3504f3, v221
	v_mul_f32_e32 v250, 0xbf3504f3, v220
	v_fmamk_f32 v226, v220, 0x3f3504f3, v241
	v_fmamk_f32 v227, v221, 0x3f3504f3, v250
	v_mul_f32_e32 v241, 0x3f800000, v221
	v_mul_f32_e32 v250, 0xbf800000, v220
	v_fmamk_f32 v232, v220, 0x00000000, v241
	v_fmamk_f32 v233, v221, 0x00000000, v250
	v_mul_f32_e32 v241, 0x3f3504f3, v221
	v_mul_f32_e32 v250, 0xbf3504f3, v220
	v_fmamk_f32 v238, v220, 0xbf3504f3, v241
	v_fmamk_f32 v239, v221, 0xbf3504f3, v250
	v_mul_f32_e32 v241, 0x3f6c835e, v223
	v_mul_f32_e32 v250, 0xbf6c835e, v222
	v_fmamk_f32 v228, v222, 0x3ec3ef15, v241
	v_fmamk_f32 v229, v223, 0x3ec3ef15, v250
	v_mul_f32_e32 v241, 0x3f3504f3, v223
	v_mul_f32_e32 v250, 0xbf3504f3, v222
	v_fmamk_f32 v234, v222, 0xbf3504f3, v241
	v_fmamk_f32 v235, v223, 0xbf3504f3, v250
	v_mul_f32_e32 v241, 0xbec3ef15, v223
	v_mul_f32_e32 v250, 0x3ec3ef15, v222
	v_fmamk_f32 v242, v222, 0xbf6c835e, v241
	v_fmamk_f32 v243, v223, 0xbf6c835e, v250
	v_pk_mul_f32 v[126:127], v[244:245], v[244:245] op_sel:[1,1] op_sel_hi:[1,0]
	s_nop 0
	v_pk_fma_f32 v[246:247], v[244:245], v[244:245], v[126:127] op_sel_hi:[0,1,1] neg_lo:[0,0,1]
	s_nop 0
	v_pk_mul_f32 v[126:127], v[246:247], v[244:245] op_sel:[1,1] op_sel_hi:[1,0]
	s_nop 0
	v_pk_fma_f32 v[248:249], v[246:247], v[244:245], v[126:127] op_sel_hi:[0,1,1] neg_lo:[0,0,1]
	s_nop 0

; DI float2 twid(float r) { return float2{__builtin_amdgcn_cosf(r), -__builtin_amdgcn_sinf(r)}; }
; DI void bfly_fwd(float2 a0, float2 a1, float2 a2, float2 a3, float r, float2& o0, float2& o1, float2& o2, float2& o3) {
;   float2 t0 = {a0.x + a2.x, a0.y + a2.y}, t1 = {a0.x - a2.x, a0.y - a2.y}, t2 = {a1.x + a3.x, a1.y + a3.y}, t3 = {a1.x - a3.x, a1.y - a3.y};
;   float2 b0 = {t0.x + t2.x, t0.y + t2.y}, b2 = {t0.x - t2.x, t0.y - t2.y}, b1 = {t1.x + t3.y, t1.y - t3.x}, b3 = {t1.x - t3.y, t1.y + t3.x};
;   float2 w1 = twid(r), w2 = cmul(w1, w1), w3 = cmul(w2, w1);
;   o0 = b0; o1 = cmul(b1, w1); o2 = cmul(b2, w2); o3 = cmul(b3, w3);
; }
;   const int lq2 = lq1 - 2, Q1 = 1 << lq1, Q2 = 1 << lq2; const float invM1 = 1.f / (float)(4 << lq1), invM2 = 1.f / (float)(4 << lq2);
;   for (int gg = tid; gg < NBT * (N / 16); gg += NTHR) { const int g = gg & (N / 16 - 1); float2* z = z0 + (gg / (N / 16)) * N; const int jp = g & (Q2 - 1), base = ((g >> lq2) << (lq2 + 4)) + jp; float2 x[4][4];
; #pragma unroll
;     for (int q1 = 0; q1 < 4; ++q1)
; #pragma unroll
;       for (int q2 = 0; q2 < 4; ++q2) x[q1][q2] = z[base + q1 * Q1 + q2 * Q2];
; #pragma unroll
;     for (int q2 = 0; q2 < 4; ++q2) bfly_fwd(x[0][q2], x[1][q2], x[2][q2], x[3][q2], (float)(jp + q2 * Q2) * invM1, x[0][q2], x[1][q2], x[2][q2], x[3][q2]);
; #pragma unroll
;     for (int q1 = 0; q1 < 4; ++q1) bfly_fwd(x[q1][0], x[q1][1], x[q1][2], x[q1][3], (float)jp * invM2, x[q1][0], x[q1][1], x[q1][2], x[q1][3]);
.LBB0_1633:
	s_or_b64 exec, exec, s[0:1]
	v_and_b32_e32 v83, 15, v76
	v_cvt_f32_ubyte0_e32 v67, v83
	v_or_b32_e32 v66, 16, v83
	v_or_b32_e32 v65, 32, v83
	v_or_b32_e32 v64, 48, v83
	s_waitcnt lgkmcnt(0)
	s_barrier
	s_and_saveexec_b64 s[0:1], vcc
	s_cbranch_execz .LBB0_1636
	v_lshlrev_b32_e32 v68, 4, v76
	s_mov_b64 s[14:15], 0
	v_mov_b32_e32 v69, v76
	v_and_b32_e32 v241, 0xf, v69
	v_cvt_f32_u32_e32 v250, v241
	v_mul_f32_e32 v250, 0x3b800000, v250
	v_cos_f32_e32 v218, v250
	v_sin_f32_e32 v219, v250
	s_nop 1
	v_xor_b32_e32 v219, 0x80000000, v219
	s_nop 0
	v_pk_mul_f32 v[130:131], v[218:219], v[218:219] op_sel:[1,1] op_sel_hi:[1,0]
	s_nop 0
	v_pk_fma_f32 v[220:221], v[218:219], v[218:219], v[130:131] op_sel_hi:[0,1,1] neg_lo:[0,0,1]
	s_nop 0
	v_pk_mul_f32 v[130:131], v[220:221], v[218:219] op_sel:[1,1] op_sel_hi:[1,0]
	s_nop 0
	v_pk_fma_f32 v[222:223], v[220:221], v[218:219], v[130:131] op_sel_hi:[0,1,1] neg_lo:[0,0,1]
	v_pk_mul_f32 v[130:131], v[220:221], v[220:221] op_sel:[1,1] op_sel_hi:[1,0]
	s_nop 0
	v_pk_fma_f32 v[244:245], v[220:221], v[220:221], v[130:131] op_sel_hi:[0,1,1] neg_lo:[0,0,1]
	s_nop 0
	v_mul_f32_e32 v241, 0x3ec3ef15, v219
	v_mul_f32_e32 v250, 0xbec3ef15, v218
	v_fmamk_f32 v224, v218, 0x3f6c835e, v241
	v_fmamk_f32 v225, v219, 0x3f6c835e, v250
	v_mul_f32_e32 v241, 0x3f3504f3, v219
	v_mul_f32_e32 v250, 0xbf3504f3, v218
	v_fmamk_f32 v230, v218, 0x3f3504f3, v241
	v_fmamk_f32 v231, v219, 0x3f3504f3, v250
	v_mul_f32_e32 v241, 0x3f6c835e, v219
	v_mul_f32_e32 v250, 0xbf6c835e, v218
	v_fmamk_f32 v236, v218, 0x3ec3ef15, v241
	v_fmamk_f32 v237, v219, 0x3ec3ef15, v250
	v_mul_f32_e32 v241, 0x3f3504f3, v221
	v_mul_f32_e32 v250, 0xbf3504f3, v220
	v_fmamk_f32 v226, v220, 0x3f3504f3, v241
	v_fmamk_f32 v227, v221, 0x3f3504f3, v250
	v_mul_f32_e32 v241, 0x3f800000, v221
	v_mul_f32_e32 v250, 0xbf800000, v220
	v_fmamk_f32 v232, v220, 0x00000000, v241
	v_fmamk_f32 v233, v221, 0x00000000, v250
	v_mul_f32_e32 v241, 0x3f3504f3, v221
	v_mul_f32_e32 v250, 0xbf3504f3, v220
	v_fmamk_f32 v238, v220, 0xbf3504f3, v241
	v_fmamk_f32 v239, v221, 0xbf3504f3, v250
	v_mul_f32_e32 v241, 0x3f6c835e, v223
	v_mul_f32_e32 v250, 0xbf6c835e, v222
	v_fmamk_f32 v228, v222, 0x3ec3ef15, v241
	v_fmamk_f32 v229, v223, 0x3ec3ef15, v250
	v_mul_f32_e32 v241, 0x3f3504f3, v223
	v_mul_f32_e32 v250, 0xbf3504f3, v222
	v_fmamk_f32 v234, v222, 0xbf3504f3, v241
	v_fmamk_f32 v235, v223, 0xbf3504f3, v250
	v_mul_f32_e32 v241, 0xbec3ef15, v223
	v_mul_f32_e32 v250, 0x3ec3ef15, v222
	v_fmamk_f32 v242, v222, 0xbf6c835e, v241
	v_fmamk_f32 v243, v223, 0xbf6c835e, v250
	v_pk_mul_f32 v[130:131], v[244:245], v[244:245] op_sel:[1,1] op_sel_hi:[1,0]
	s_nop 0
	v_pk_fma_f32 v[246:247], v[244:245], v[244:245], v[130:131] op_sel_hi:[0,1,1] neg_lo:[0,0,1]
	s_nop 0
	v_pk_mul_f32 v[130:131], v[246:247], v[244:245] op_sel:[1,1] op_sel_hi:[1,0]
	s_nop 0
	v_pk_fma_f32 v[248:249], v[246:247], v[244:245], v[130:131] op_sel_hi:[0,1,1] neg_lo:[0,0,1]
	s_nop 0

; DI float2 twid(float r) { return float2{__builtin_amdgcn_cosf(r), -__builtin_amdgcn_sinf(r)}; }
; DI void bfly_inv(float2 s0, float2 s1, float2 s2, float2 s3, float r, float2& o0, float2& o1, float2& o2, float2& o3) {
;   float2 w1 = twid(r), w2 = cmul(w1, w1), w3 = cmul(w2, w1);
;   float2 c0 = s0, c1 = cmulc(s1, w1), c2 = cmulc(s2, w2), c3 = cmulc(s3, w3);
;   const int lq1 = lq2 + 2, Q1 = 1 << lq1, Q2 = 1 << lq2; const float invM1 = 1.f / (float)(4 << lq1), invM2 = 1.f / (float)(4 << lq2);
;   for (int gg = tid; gg < NBT * (N / 16); gg += NTHR) { const int g = gg & (N / 16 - 1); float2* z = z0 + (gg / (N / 16)) * N; const int jp = g & (Q2 - 1), base = ((g >> lq2) << (lq2 + 4)) + jp; float2 x[4][4];
; #pragma unroll
;     for (int q1 = 0; q1 < 4; ++q1)
; #pragma unroll
;       for (int q2 = 0; q2 < 4; ++q2) x[q1][q2] = z[base + q1 * Q1 + q2 * Q2];
; #pragma unroll
;     for (int q1 = 0; q1 < 4; ++q1) bfly_inv(x[q1][0], x[q1][1], x[q1][2], x[q1][3], (float)jp * invM2, x[q1][0], x[q1][1], x[q1][2], x[q1][3]);
; #pragma unroll
;     for (int q2 = 0; q2 < 4; ++q2) bfly_inv(x[0][q2], x[1][q2], x[2][q2], x[3][q2], (float)(jp + q2 * Q2) * invM1, x[0][q2], x[1][q2], x[2][q2], x[3][q2]);
.LBB0_1648:
	s_or_b64 exec, exec, s[0:1]
	s_waitcnt lgkmcnt(0)
	s_barrier
	s_and_saveexec_b64 s[14:15], vcc
	s_cbranch_execz .LBB0_1651
	s_mov_b64 s[0:1], 0
	v_mov_b32_e32 v84, v76
	v_lshlrev_b32_e32 v62, 4, v76
	v_and_b32_e32 v241, 0xf, v84
	v_cvt_f32_u32_e32 v250, v241
	v_mul_f32_e32 v250, 0x3b800000, v250
	v_cos_f32_e32 v218, v250
	v_sin_f32_e32 v219, v250
	s_nop 1
	s_nop 0
	v_pk_mul_f32 v[134:135], v[218:219], v[218:219] op_sel:[1,1] op_sel_hi:[1,0]
	s_nop 0
	v_pk_fma_f32 v[220:221], v[218:219], v[218:219], v[134:135] op_sel_hi:[0,1,1] neg_lo:[0,0,1]
	s_nop 0
	v_pk_mul_f32 v[134:135], v[220:221], v[218:219] op_sel:[1,1] op_sel_hi:[1,0]
	s_nop 0
	v_pk_fma_f32 v[222:223], v[220:221], v[218:219], v[134:135] op_sel_hi:[0,1,1] neg_lo:[0,0,1]
	v_pk_mul_f32 v[134:135], v[220:221], v[220:221] op_sel:[1,1] op_sel_hi:[1,0]
	s_nop 0
	v_pk_fma_f32 v[244:245], v[220:221], v[220:221], v[134:135] op_sel_hi:[0,1,1] neg_lo:[0,0,1]
	s_nop 0
	v_mul_f32_e32 v241, 0xbec3ef15, v219
	v_mul_f32_e32 v250, 0x3ec3ef15, v218
	v_fmamk_f32 v224, v218, 0x3f6c835e, v241
	v_fmamk_f32 v225, v219, 0x3f6c835e, v250
	v_mul_f32_e32 v241, 0xbf3504f3, v219
	v_mul_f32_e32 v250, 0x3f3504f3, v218
	v_fmamk_f32 v230, v218, 0x3f3504f3, v241
	v_fmamk_f32 v231, v219, 0x3f3504f3, v250
	v_mul_f32_e32 v241, 0xbf6c835e, v219
	v_mul_f32_e32 v250, 0x3f6c835e, v218
	v_fmamk_f32 v236, v218, 0x3ec3ef15, v241
	v_fmamk_f32 v237, v219, 0x3ec3ef15, v250
	v_mul_f32_e32 v241, 0xbf3504f3, v221
	v_mul_f32_e32 v250, 0x3f3504f3, v220
	v_fmamk_f32 v226, v220, 0x3f3504f3, v241
	v_fmamk_f32 v227, v221, 0x3f3504f3, v250
	v_mul_f32_e32 v241, 0xbf800000, v221
	v_mul_f32_e32 v250, 0x3f800000, v220
	v_fmamk_f32 v232, v220, 0x00000000, v241
	v_fmamk_f32 v233, v221, 0x00000000, v250
	v_mul_f32_e32 v241, 0xbf3504f3, v221
	v_mul_f32_e32 v250, 0x3f3504f3, v220
	v_fmamk_f32 v238, v220, 0xbf3504f3, v241
	v_fmamk_f32 v239, v221, 0xbf3504f3, v250
	v_mul_f32_e32 v241, 0xbf6c835e, v223
	v_mul_f32_e32 v250, 0x3f6c835e, v222
	v_fmamk_f32 v228, v222, 0x3ec3ef15, v241
	v_fmamk_f32 v229, v223, 0x3ec3ef15, v250
	v_mul_f32_e32 v241, 0xbf3504f3, v223
	v_mul_f32_e32 v250, 0x3f3504f3, v222
	v_fmamk_f32 v234, v222, 0xbf3504f3, v241
	v_fmamk_f32 v235, v223, 0xbf3504f3, v250
	v_mul_f32_e32 v241, 0x3ec3ef15, v223
	v_mul_f32_e32 v250, 0xbec3ef15, v222
	v_fmamk_f32 v242, v222, 0xbf6c835e, v241
	v_fmamk_f32 v243, v223, 0xbf6c835e, v250
	v_pk_mul_f32 v[134:135], v[244:245], v[244:245] op_sel:[1,1] op_sel_hi:[1,0]
	s_nop 0
	v_pk_fma_f32 v[246:247], v[244:245], v[244:245], v[134:135] op_sel_hi:[0,1,1] neg_lo:[0,0,1]
	s_nop 0
	v_pk_mul_f32 v[134:135], v[246:247], v[244:245] op_sel:[1,1] op_sel_hi:[1,0]
	s_nop 0
	v_pk_fma_f32 v[248:249], v[246:247], v[244:245], v[134:135] op_sel_hi:[0,1,1] neg_lo:[0,0,1]
	s_nop 0

; DI float2 twid(float r) { return float2{__builtin_amdgcn_cosf(r), -__builtin_amdgcn_sinf(r)}; }
; DI void bfly_inv(float2 s0, float2 s1, float2 s2, float2 s3, float r, float2& o0, float2& o1, float2& o2, float2& o3) {
;   float2 w1 = twid(r), w2 = cmul(w1, w1), w3 = cmul(w2, w1);
;   float2 c0 = s0, c1 = cmulc(s1, w1), c2 = cmulc(s2, w2), c3 = cmulc(s3, w3);
;   const int lq1 = lq2 + 2, Q1 = 1 << lq1, Q2 = 1 << lq2; const float invM1 = 1.f / (float)(4 << lq1), invM2 = 1.f / (float)(4 << lq2);
;   for (int gg = tid; gg < NBT * (N / 16); gg += NTHR) { const int g = gg & (N / 16 - 1); float2* z = z0 + (gg / (N / 16)) * N; const int jp = g & (Q2 - 1), base = ((g >> lq2) << (lq2 + 4)) + jp; float2 x[4][4];
; #pragma unroll
;     for (int q1 = 0; q1 < 4; ++q1)
; #pragma unroll
;       for (int q2 = 0; q2 < 4; ++q2) x[q1][q2] = z[base + q1 * Q1 + q2 * Q2];
; #pragma unroll
;     for (int q1 = 0; q1 < 4; ++q1) bfly_inv(x[q1][0], x[q1][1], x[q1][2], x[q1][3], (float)jp * invM2, x[q1][0], x[q1][1], x[q1][2], x[q1][3]);
; #pragma unroll
;     for (int q2 = 0; q2 < 4; ++q2) bfly_inv(x[0][q2], x[1][q2], x[2][q2], x[3][q2], (float)(jp + q2 * Q2) * invM1, x[0][q2], x[1][q2], x[2][q2], x[3][q2]);
.LBB0_1651:
	s_or_b64 exec, exec, s[14:15]
	s_waitcnt lgkmcnt(0)
	s_barrier
	s_and_saveexec_b64 s[12:13], vcc
	s_cbranch_execz .LBB0_1654
	v_cvt_f32_u32_e32 v11, v79
	v_mul_f32_e32 v8, 0x39800000, v11
	v_sin_f32_e32 v35, v8
	v_cos_f32_e32 v37, v8
	v_mul_f32_e32 v8, v35, v35
	v_fma_f32 v38, v37, v37, -v8
	v_mul_f32_e64 v8, v37, -v35
	v_add_f32_e32 v40, v8, v8
	v_mul_f32_e32 v34, v35, v40
	v_fmac_f32_e32 v34, v37, v38
	v_pk_mov_b32 v[54:55], v[36:37], v[34:35] op_sel:[1,0]
	s_mov_b64 s[0:1], 0
	v_mov_b32_e32 v62, v76
	v_and_b32_e32 v241, 0xff, v62
	v_cvt_f32_u32_e32 v250, v241
	v_mul_f32_e32 v250, 0x39800000, v250
	v_cos_f32_e32 v218, v250
	v_sin_f32_e32 v219, v250
	s_nop 1
	s_nop 0
	v_pk_mul_f32 v[128:129], v[218:219], v[218:219] op_sel:[1,1] op_sel_hi:[1,0]
	s_nop 0
	v_pk_fma_f32 v[220:221], v[218:219], v[218:219], v[128:129] op_sel_hi:[0,1,1] neg_lo:[0,0,1]
	s_nop 0
	v_pk_mul_f32 v[128:129], v[220:221], v[218:219] op_sel:[1,1] op_sel_hi:[1,0]
	s_nop 0
	v_pk_fma_f32 v[222:223], v[220:221], v[218:219], v[128:129] op_sel_hi:[0,1,1] neg_lo:[0,0,1]
	v_pk_mul_f32 v[128:129], v[220:221], v[220:221] op_sel:[1,1] op_sel_hi:[1,0]
	s_nop 0
	v_pk_fma_f32 v[244:245], v[220:221], v[220:221], v[128:129] op_sel_hi:[0,1,1] neg_lo:[0,0,1]
	s_nop 0
	v_mul_f32_e32 v241, 0xbec3ef15, v219
	v_mul_f32_e32 v250, 0x3ec3ef15, v218
	v_fmamk_f32 v224, v218, 0x3f6c835e, v241
	v_fmamk_f32 v225, v219, 0x3f6c835e, v250
	v_mul_f32_e32 v241, 0xbf3504f3, v219
	v_mul_f32_e32 v250, 0x3f3504f3, v218
	v_fmamk_f32 v230, v218, 0x3f3504f3, v241
	v_fmamk_f32 v231, v219, 0x3f3504f3, v250
	v_mul_f32_e32 v241, 0xbf6c835e, v219
	v_mul_f32_e32 v250, 0x3f6c835e, v218
	v_fmamk_f32 v236, v218, 0x3ec3ef15, v241
	v_fmamk_f32 v237, v219, 0x3ec3ef15, v250
	v_mul_f32_e32 v241, 0xbf3504f3, v221
	v_mul_f32_e32 v250, 0x3f3504f3, v220
	v_fmamk_f32 v226, v220, 0x3f3504f3, v241
	v_fmamk_f32 v227, v221, 0x3f3504f3, v250
	v_mul_f32_e32 v241, 0xbf800000, v221
	v_mul_f32_e32 v250, 0x3f800000, v220
	v_fmamk_f32 v232, v220, 0x00000000, v241
	v_fmamk_f32 v233, v221, 0x00000000, v250
	v_mul_f32_e32 v241, 0xbf3504f3, v221
	v_mul_f32_e32 v250, 0x3f3504f3, v220
	v_fmamk_f32 v238, v220, 0xbf3504f3, v241
	v_fmamk_f32 v239, v221, 0xbf3504f3, v250
	v_mul_f32_e32 v241, 0xbf6c835e, v223
	v_mul_f32_e32 v250, 0x3f6c835e, v222
	v_fmamk_f32 v228, v222, 0x3ec3ef15, v241
	v_fmamk_f32 v229, v223, 0x3ec3ef15, v250
	v_mul_f32_e32 v241, 0xbf3504f3, v223
	v_mul_f32_e32 v250, 0x3f3504f3, v222
	v_fmamk_f32 v234, v222, 0xbf3504f3, v241
	v_fmamk_f32 v235, v223, 0xbf3504f3, v250
	v_mul_f32_e32 v241, 0x3ec3ef15, v223
	v_mul_f32_e32 v250, 0xbec3ef15, v222
	v_fmamk_f32 v242, v222, 0xbf6c835e, v241
	v_fmamk_f32 v243, v223, 0xbf6c835e, v250
	v_pk_mul_f32 v[128:129], v[244:245], v[244:245] op_sel:[1,1] op_sel_hi:[1,0]
	s_nop 0
	v_pk_fma_f32 v[246:247], v[244:245], v[244:245], v[128:129] op_sel_hi:[0,1,1] neg_lo:[0,0,1]
	s_nop 0
	v_pk_mul_f32 v[128:129], v[246:247], v[244:245] op_sel:[1,1] op_sel_hi:[1,0]
	s_nop 0
	v_pk_fma_f32 v[248:249], v[246:247], v[244:245], v[128:129] op_sel_hi:[0,1,1] neg_lo:[0,0,1]
	s_nop 0
